# ResNorm final-output f32 stores (last phase) also written as whole 128-byte lines through the LDS ring
# speedup vs baseline: 1.0373x; 1.0048x over previous
.LBB0_938:
	v_readfirstlane_b32 s100, v192
	s_lshl_b32 s98, s22, 20
	s_lshr_b32 s99, s22, 12
	s_add_u32 s98, s98, s76
	s_addc_u32 s99, s99, s77
	s_mul_i32 s100, s100, 192
	s_add_i32 s100, s100, 0x4000
	v_and_b32_e32 v172, 15, v219
	v_lshrrev_b32_e32 v173, 4, v219
	v_and_b32_e32 v164, 7, v172
	v_xor_b32_e32 v173, v173, v164
	v_lshlrev_b32_e32 v164, 7, v172
	v_add_u32_e32 v164, s100, v164
	v_xor_b32_e32 v165, 4, v173
	v_lshl_add_u32 v165, v165, 4, v164
	v_lshl_add_u32 v164, v173, 4, v164
	v_lshlrev_b32_e32 v168, 4, v219
	v_add_u32_e32 v168, s100, v168
	v_lshrrev_b32_e32 v172, 3, v219
	v_and_b32_e32 v173, 7, v219
	v_xor_b32_e32 v173, v173, v172
	v_and_b32_e32 v169, 0xc0, v160
	v_add_u32_e32 v169, v169, v172
	v_lshlrev_b32_e32 v169, 12, v169
	v_lshl_or_b32 v169, v173, 4, v169
	v_and_b32_e32 v172, 0xfffffff3, v210
	v_lshl_add_u32 v169, v172, 2, v169
	v_lshl_add_u32 v178, v160, 2, 0
	v_cndmask_b32_e64 v161, 0, 1, s[20:21]
	v_bfe_u32 v250, v224, 4, 1
	v_mov_b32_e32 v251, 0
	v_cmp_ne_u32_e64 s[38:39], 1, v161
	v_mul_u32_u24_e32 v250, 24, v250
	s_lshl_b64 s[0:1], s[22:23], 19
	v_readlane_b32 s2, v254, 53
	v_readlane_b32 s3, v254, 54
	s_add_u32 s2, s2, s0
	s_addc_u32 s3, s3, s1
	s_waitcnt vmcnt(0)
	ds_read_b32 v242, v178 offset:8192
	ds_read_b32 v244, v178 offset:8256
	ds_read_b32 v246, v178 offset:8320
	ds_read_b32 v184, v178 offset:8384
	ds_read_b32 v212, v178 offset:8704
	ds_read_b32 v210, v178 offset:8768
	ds_read_b32 v160, v178 offset:8832
	ds_read_b32 v224, v178 offset:8896
	s_waitcnt lgkmcnt(7)
	v_pk_mul_f32 v[226:227], v[156:157], v[242:243] op_sel_hi:[1,0]
	v_pk_mul_f32 v[228:229], v[158:159], v[242:243] op_sel_hi:[1,0]
	v_pk_mul_f32 v[230:231], v[152:153], v[242:243] op_sel_hi:[1,0]
	v_pk_mul_f32 v[232:233], v[154:155], v[242:243] op_sel_hi:[1,0]
	v_pk_mul_f32 v[234:235], v[148:149], v[242:243] op_sel_hi:[1,0]
	v_pk_mul_f32 v[236:237], v[150:151], v[242:243] op_sel_hi:[1,0]
	v_pk_mul_f32 v[238:239], v[116:117], v[242:243] op_sel_hi:[1,0]
	v_pk_mul_f32 v[240:241], v[118:119], v[242:243] op_sel_hi:[1,0]
	v_pk_fma_f32 v[226:227], v[128:129], v[226:227], v[140:141]
	v_pk_fma_f32 v[228:229], v[130:131], v[228:229], v[142:143]
	v_pk_fma_f32 v[230:231], v[136:137], v[230:231], v[108:109]
	v_pk_fma_f32 v[232:233], v[138:139], v[232:233], v[110:111]
	v_pk_fma_f32 v[234:235], v[120:121], v[234:235], v[132:133]
	v_pk_fma_f32 v[236:237], v[122:123], v[236:237], v[134:135]
	v_pk_fma_f32 v[238:239], v[112:113], v[238:239], v[100:101]
	v_pk_fma_f32 v[240:241], v[114:115], v[240:241], v[102:103]
	s_and_b64 vcc, exec, s[38:39]
	s_cbranch_vccz .Lrn2_fin_0
	v_lshl_add_u64 v[248:249], v[206:207], 1, s[2:3]
	v_cvt_pk_bf16_f32 v226, v226, v227
	v_cvt_pk_bf16_f32 v227, v228, v229
	v_cvt_pk_bf16_f32 v228, v230, v231
	v_cvt_pk_bf16_f32 v229, v232, v233
	v_lshl_add_u64 v[248:249], v[248:249], 0, v[250:251]
	s_nop 0
	v_permlane16_swap_b32 v226, v228
	v_permlane16_swap_b32 v227, v229
	global_store_dwordx4 v[248:249], v[226:229], off
	v_cvt_pk_bf16_f32 v234, v234, v235
	v_cvt_pk_bf16_f32 v235, v236, v237
	v_cvt_pk_bf16_f32 v236, v238, v239
	v_cvt_pk_bf16_f32 v237, v240, v241
	s_nop 1
	v_permlane16_swap_b32 v234, v236
	v_permlane16_swap_b32 v235, v237
	global_store_dwordx4 v[248:249], v[234:237], off offset:256
	s_branch .Lrn2_nx_0
.Lrn2_fin_0:
	ds_write_b128 v164, v[226:229] offset:0
	ds_write_b128 v165, v[230:233] offset:0
	ds_write_b128 v164, v[234:237] offset:2048
	ds_write_b128 v165, v[238:241] offset:2048
	s_waitcnt lgkmcnt(0)
	ds_read_b128 v[226:229], v168 offset:0
	ds_read_b128 v[230:233], v168 offset:1024
	ds_read_b128 v[234:237], v168 offset:2048
	ds_read_b128 v[238:241], v168 offset:3072
	s_add_u32 s100, s98, 0x0
	s_addc_u32 s101, s99, 0
	s_waitcnt lgkmcnt(3)
	global_store_dwordx4 v169, v[226:229], s[100:101] nt
	s_add_u32 s100, s98, 0x8000
	s_addc_u32 s101, s99, 0
	s_waitcnt lgkmcnt(2)
	global_store_dwordx4 v169, v[230:233], s[100:101] nt
	s_add_u32 s100, s98, 0x200
	s_addc_u32 s101, s99, 0
	s_waitcnt lgkmcnt(1)
	global_store_dwordx4 v169, v[234:237], s[100:101] nt
	s_add_u32 s100, s98, 0x8200
	s_addc_u32 s101, s99, 0
	s_waitcnt lgkmcnt(0)
	global_store_dwordx4 v169, v[238:241], s[100:101] nt

.Lrn2_fin_1:
	ds_write_b128 v164, v[156:159] offset:4096
	ds_write_b128 v165, v[152:155] offset:4096
	ds_write_b128 v164, v[148:151] offset:6144
	ds_write_b128 v165, v[116:119] offset:6144
	s_waitcnt lgkmcnt(0)
	ds_read_b128 v[156:159], v168 offset:4096
	ds_read_b128 v[152:155], v168 offset:5120
	ds_read_b128 v[148:151], v168 offset:6144
	ds_read_b128 v[116:119], v168 offset:7168
	s_add_u32 s100, s98, 0x10000
	s_addc_u32 s101, s99, 0
	s_waitcnt lgkmcnt(3)
	global_store_dwordx4 v169, v[156:159], s[100:101] nt
	s_add_u32 s100, s98, 0x18000
	s_addc_u32 s101, s99, 0
	s_waitcnt lgkmcnt(2)
	global_store_dwordx4 v169, v[152:155], s[100:101] nt
	s_add_u32 s100, s98, 0x10200
	s_addc_u32 s101, s99, 0
	s_waitcnt lgkmcnt(1)
	global_store_dwordx4 v169, v[148:151], s[100:101] nt
	s_add_u32 s100, s98, 0x18200
	s_addc_u32 s101, s99, 0
	s_waitcnt lgkmcnt(0)
	global_store_dwordx4 v169, v[116:119], s[100:101] nt

.Lrn2_fin_2:
	ds_write_b128 v164, v[226:229] offset:8192
	ds_write_b128 v165, v[230:233] offset:8192
	ds_write_b128 v164, v[234:237] offset:10240
	ds_write_b128 v165, v[238:241] offset:10240
	s_waitcnt lgkmcnt(0)
	ds_read_b128 v[226:229], v168 offset:8192
	ds_read_b128 v[230:233], v168 offset:9216
	ds_read_b128 v[234:237], v168 offset:10240
	ds_read_b128 v[238:241], v168 offset:11264
	s_add_u32 s100, s98, 0x20000
	s_addc_u32 s101, s99, 0
	s_waitcnt lgkmcnt(3)
	global_store_dwordx4 v169, v[226:229], s[100:101] nt
	s_add_u32 s100, s98, 0x28000
	s_addc_u32 s101, s99, 0
	s_waitcnt lgkmcnt(2)
	global_store_dwordx4 v169, v[230:233], s[100:101] nt
	s_add_u32 s100, s98, 0x20200
	s_addc_u32 s101, s99, 0
	s_waitcnt lgkmcnt(1)
	global_store_dwordx4 v169, v[234:237], s[100:101] nt
	s_add_u32 s100, s98, 0x28200
	s_addc_u32 s101, s99, 0
	s_waitcnt lgkmcnt(0)
	global_store_dwordx4 v169, v[238:241], s[100:101] nt

.Lrn2_fin_3:
	ds_write_b128 v164, v[156:159] offset:0
	ds_write_b128 v165, v[152:155] offset:0
	ds_write_b128 v164, v[148:151] offset:2048
	ds_write_b128 v165, v[116:119] offset:2048
	s_waitcnt lgkmcnt(0)
	ds_read_b128 v[156:159], v168 offset:0
	ds_read_b128 v[152:155], v168 offset:1024
	ds_read_b128 v[148:151], v168 offset:2048
	ds_read_b128 v[116:119], v168 offset:3072
	s_add_u32 s100, s98, 0x30000
	s_addc_u32 s101, s99, 0
	s_waitcnt lgkmcnt(3)
	global_store_dwordx4 v169, v[156:159], s[100:101] nt
	s_add_u32 s100, s98, 0x38000
	s_addc_u32 s101, s99, 0
	s_waitcnt lgkmcnt(2)
	global_store_dwordx4 v169, v[152:155], s[100:101] nt
	s_add_u32 s100, s98, 0x30200
	s_addc_u32 s101, s99, 0
	s_waitcnt lgkmcnt(1)
	global_store_dwordx4 v169, v[148:151], s[100:101] nt
	s_add_u32 s100, s98, 0x38200
	s_addc_u32 s101, s99, 0
	s_waitcnt lgkmcnt(0)
	global_store_dwordx4 v169, v[116:119], s[100:101] nt

.Lrn2_fin_4:
	ds_write_b128 v164, v[226:229] offset:4096
	ds_write_b128 v165, v[230:233] offset:4096
	ds_write_b128 v164, v[234:237] offset:6144
	ds_write_b128 v165, v[238:241] offset:6144
	s_waitcnt lgkmcnt(0)
	ds_read_b128 v[226:229], v168 offset:4096
	ds_read_b128 v[230:233], v168 offset:5120
	ds_read_b128 v[234:237], v168 offset:6144
	ds_read_b128 v[238:241], v168 offset:7168
	s_add_u32 s100, s98, 0x80000
	s_addc_u32 s101, s99, 0
	s_waitcnt lgkmcnt(3)
	global_store_dwordx4 v169, v[226:229], s[100:101] nt
	s_add_u32 s100, s98, 0x88000
	s_addc_u32 s101, s99, 0
	s_waitcnt lgkmcnt(2)
	global_store_dwordx4 v169, v[230:233], s[100:101] nt
	s_add_u32 s100, s98, 0x80200
	s_addc_u32 s101, s99, 0
	s_waitcnt lgkmcnt(1)
	global_store_dwordx4 v169, v[234:237], s[100:101] nt
	s_add_u32 s100, s98, 0x88200
	s_addc_u32 s101, s99, 0
	s_waitcnt lgkmcnt(0)
	global_store_dwordx4 v169, v[238:241], s[100:101] nt

.Lrn2_fin_5:
	ds_write_b128 v164, v[156:159] offset:8192
	ds_write_b128 v165, v[152:155] offset:8192
	ds_write_b128 v164, v[148:151] offset:10240
	ds_write_b128 v165, v[116:119] offset:10240
	s_waitcnt lgkmcnt(0)
	ds_read_b128 v[156:159], v168 offset:8192
	ds_read_b128 v[152:155], v168 offset:9216
	ds_read_b128 v[148:151], v168 offset:10240
	ds_read_b128 v[116:119], v168 offset:11264
	s_add_u32 s100, s98, 0x90000
	s_addc_u32 s101, s99, 0
	s_waitcnt lgkmcnt(3)
	global_store_dwordx4 v169, v[156:159], s[100:101] nt
	s_add_u32 s100, s98, 0x98000
	s_addc_u32 s101, s99, 0
	s_waitcnt lgkmcnt(2)
	global_store_dwordx4 v169, v[152:155], s[100:101] nt
	s_add_u32 s100, s98, 0x90200
	s_addc_u32 s101, s99, 0
	s_waitcnt lgkmcnt(1)
	global_store_dwordx4 v169, v[148:151], s[100:101] nt
	s_add_u32 s100, s98, 0x98200
	s_addc_u32 s101, s99, 0
	s_waitcnt lgkmcnt(0)
	global_store_dwordx4 v169, v[116:119], s[100:101] nt

.Lrn2_fin_6:
	ds_write_b128 v164, v[226:229] offset:0
	ds_write_b128 v165, v[230:233] offset:0
	ds_write_b128 v164, v[234:237] offset:2048
	ds_write_b128 v165, v[238:241] offset:2048
	s_waitcnt lgkmcnt(0)
	ds_read_b128 v[226:229], v168 offset:0
	ds_read_b128 v[230:233], v168 offset:1024
	ds_read_b128 v[234:237], v168 offset:2048
	ds_read_b128 v[238:241], v168 offset:3072
	s_add_u32 s100, s98, 0xa0000
	s_addc_u32 s101, s99, 0
	s_waitcnt lgkmcnt(3)
	global_store_dwordx4 v169, v[226:229], s[100:101] nt
	s_add_u32 s100, s98, 0xa8000
	s_addc_u32 s101, s99, 0
	s_waitcnt lgkmcnt(2)
	global_store_dwordx4 v169, v[230:233], s[100:101] nt
	s_add_u32 s100, s98, 0xa0200
	s_addc_u32 s101, s99, 0
	s_waitcnt lgkmcnt(1)
	global_store_dwordx4 v169, v[234:237], s[100:101] nt
	s_add_u32 s100, s98, 0xa8200
	s_addc_u32 s101, s99, 0
	s_waitcnt lgkmcnt(0)
	global_store_dwordx4 v169, v[238:241], s[100:101] nt

.Lrn2_fin_7:
	ds_write_b128 v164, v[156:159] offset:4096
	ds_write_b128 v165, v[152:155] offset:4096
	ds_write_b128 v164, v[148:151] offset:6144
	ds_write_b128 v165, v[116:119] offset:6144
	s_waitcnt lgkmcnt(0)
	ds_read_b128 v[156:159], v168 offset:4096
	ds_read_b128 v[152:155], v168 offset:5120
	ds_read_b128 v[148:151], v168 offset:6144
	ds_read_b128 v[116:119], v168 offset:7168
	s_add_u32 s100, s98, 0xb0000
	s_addc_u32 s101, s99, 0
	s_waitcnt lgkmcnt(3)
	global_store_dwordx4 v169, v[156:159], s[100:101] nt
	s_add_u32 s100, s98, 0xb8000
	s_addc_u32 s101, s99, 0
	s_waitcnt lgkmcnt(2)
	global_store_dwordx4 v169, v[152:155], s[100:101] nt
	s_add_u32 s100, s98, 0xb0200
	s_addc_u32 s101, s99, 0
	s_waitcnt lgkmcnt(1)
	global_store_dwordx4 v169, v[148:151], s[100:101] nt
	s_add_u32 s100, s98, 0xb8200
	s_addc_u32 s101, s99, 0
	s_waitcnt lgkmcnt(0)
	global_store_dwordx4 v169, v[116:119], s[100:101] nt
